# deferred weight conversion with 592 items per barrier (18 barriers carry work instead of 14, less per barrier)
# speedup vs baseline: 1.0106x; 1.0106x over previous
; #define LAS __attribute__((address_space(3)))
; __device__ __forceinline__ void prologue(const Args& a, LAS unsigned char* lds, int vcu, int G, int wave, int lane, int tid) {
;     unsigned char* ws = a.ws;
;     LAS float* scr = (LAS float*)(lds + wave * XP_WAVE_BYTES);
;     const int gw = vcu * NWAVES + wave, NGW = G * NWAVES;
;     constexpr int I_QKV = 16 * 48, I_SQ = 16 * 16, I_POOL = 4 * 4, I_UP = 16 * 64, I_DN = 64 * 16;
;     constexpr int NITEMS = 2 * I_QKV + 2 * I_SQ + 4 * I_POOL + I_QKV + I_SQ + 4 * I_UP + 4 * I_DN;
;     const float* nmix = a.in[2]; const float* nmlp = a.in[3];
;     for (int it = gw; it < NITEMS; it += NGW) {
;         int r = it;
;         if (r < 2 * I_QKV) { const int l = r / I_QKV; r -= l * I_QKV; xpose_item(a.in[4] + (size_t)l * 1024 * 3072, 1024, 3072, (bf16*)(ws + WS_WQKV) + (size_t)l * 3072 * 1024, nmix + (l ? 3 : 0) * 1024, 4, scr, r, lane); continue; } r -= 2 * I_QKV;
;         if (r < 2 * I_SQ) { const int l = r / I_SQ; r -= l * I_SQ; xpose_item(a.in[5] + (size_t)l * 1024 * 1024, 1024, 1024, (bf16*)(ws + WS_WO) + (size_t)l * 1024 * 1024, nullptr, 4, scr, r, lane); continue; } r -= 2 * I_SQ;
;         if (r < 4 * I_POOL) { const int g = r / I_POOL; r -= g * I_POOL; xpose_item(a.in[6] + (size_t)g * 65536, 256, 256, (bf16*)(ws + WS_WPOOL) + (size_t)g * 65536, nullptr, 4, scr, r, lane); continue; } r -= 4 * I_POOL;
;         if (r < I_QKV) { xpose_item(a.in[8], 1024, 3072, (bf16*)(ws + WS_WCI), nmix + 2 * 1024, 1, scr, r, lane); continue; } r -= I_QKV;
;         if (r < I_SQ) { xpose_item(a.in[10], 1024, 1024, (bf16*)(ws + WS_WCO), nullptr, 4, scr, r, lane); continue; } r -= I_SQ;
;         if (r < 4 * I_UP) { const int l = r / I_UP; r -= l * I_UP; xpose_item(a.in[11] + (size_t)l * 1024 * 4096, 1024, 4096, (bf16*)(ws + WS_WUP) + (size_t)l * 4096 * 1024, nmlp + l * 1024, 4, scr, r, lane); continue; } r -= 4 * I_UP;
;         { const int l = r / I_DN; r -= l * I_DN; xpose_item(a.in[12] + (size_t)l * 4096 * 1024, 4096, 1024, (bf16*)(ws + WS_WDN) + (size_t)l * 1024 * 4096, nullptr, 4, scr, r, lane); }
;     }
.Lmy_items:
	s_mov_b64 exec, -1
	v_readlane_b32 s65, v253, 2
	s_cmp_lg_u32 s65, 0x100
	s_cbranch_scc1 .LBB0_633
	v_readfirstlane_b32 s3, v0
	s_lshr_b32 s3, s3, 6
	s_cmp_gt_u32 s3, 3
	s_cbranch_scc1 .LBB0_633
	v_writelane_b32 v200, s0, 0
	v_writelane_b32 v200, s1, 1
	v_writelane_b32 v200, s2, 2
	v_writelane_b32 v200, s3, 3
	v_writelane_b32 v200, s4, 4
	v_writelane_b32 v200, s5, 5
	v_writelane_b32 v200, s6, 6
	v_writelane_b32 v200, s7, 7
	v_writelane_b32 v200, s8, 8
	v_writelane_b32 v200, s9, 9
	v_writelane_b32 v200, s10, 10
	v_writelane_b32 v200, s11, 11
	v_writelane_b32 v200, s12, 12
	v_writelane_b32 v200, s13, 13
	v_writelane_b32 v200, s14, 14
	v_writelane_b32 v200, s15, 15
	v_writelane_b32 v200, s16, 16
	v_writelane_b32 v200, s17, 17
	v_writelane_b32 v200, s18, 18
	v_writelane_b32 v200, s19, 19
	v_writelane_b32 v200, s68, 20
	v_writelane_b32 v200, s69, 21
	v_writelane_b32 v200, s70, 22
	v_writelane_b32 v200, s71, 23
	v_writelane_b32 v200, s72, 24
	v_writelane_b32 v200, s73, 25
	v_writelane_b32 v200, s74, 26
	v_writelane_b32 v200, s75, 27
	v_writelane_b32 v200, s76, 28
	v_writelane_b32 v200, s77, 29
	v_writelane_b32 v200, s78, 30
	v_writelane_b32 v200, s79, 31
	v_writelane_b32 v200, s80, 32
	v_writelane_b32 v200, s81, 33
	v_writelane_b32 v200, s82, 34
	v_writelane_b32 v200, s83, 35
	v_writelane_b32 v200, s86, 36
	s_add_i32 s2, s66, -1
	s_add_i32 s4, s66, -2
	s_cmp_gt_u32 s66, 8
	s_cselect_b32 s2, s4, s2
	s_add_i32 s5, s3, -1
	s_lshl_b32 s5, s5, 8
	v_readlane_b32 s6, v255, 47
	s_lshr_b32 s7, s6, 3
	s_add_i32 s5, s5, s7
	s_cmp_ge_u32 s5, 592
	s_cbranch_scc1 .Lmy_items_restore
	s_mul_i32 s2, s2, 592
	s_add_i32 s2, s2, s5
	s_cmp_ge_u32 s2, 10560
	s_cbranch_scc1 .Lmy_items_restore
	s_mov_b32 s4, 1536
	s_cmp_ge_u32 s2, 256
	s_cselect_b32 s4, 2880, s4
	s_cmp_ge_u32 s2, 1280
	s_cselect_b32 s4, 5952, s4
	s_cmp_ge_u32 s2, 2304
	s_cselect_b32 s4, -256, s4
	s_cmp_ge_u32 s2, 2368
	s_cselect_b32 s4, 1792, s4
	s_cmp_ge_u32 s2, 3392
	s_cselect_b32 s4, 4864, s4
	s_cmp_ge_u32 s2, 4416
	s_cselect_b32 s4, -2304, s4
	s_cmp_ge_u32 s2, 5184
	s_cselect_b32 s4, -2304, s4
	s_cmp_ge_u32 s2, 5440
	s_cselect_b32 s4, -256, s4
	s_cmp_ge_u32 s2, 6464
	s_cselect_b32 s4, 2816, s4
	s_cmp_ge_u32 s2, 7488
	s_cselect_b32 s4, -6720, s4
	s_cmp_ge_u32 s2, 8256
	s_cselect_b32 s4, -6464, s4
	s_cmp_ge_u32 s2, 8512
	s_cselect_b32 s4, -2304, s4
	s_cmp_ge_u32 s2, 9536
	s_cselect_b32 s4, 768, s4
	s_add_i32 s19, s2, s4
	v_mov_b32_e32 v221, v0
	v_readlane_b32 s65, v253, 2
	s_mov_b32 s70, s3
	s_mov_b32 s85, s6
	v_readlane_b32 s28, v255, 48
	s_add_i32 s0, s70, s85
	s_sub_i32 s19, s19, s0
	s_lshl_b32 s12, s65, 3
	v_and_b32_e32 v2, 63, v221
	v_lshlrev_b32_e32 v66, 2, v2
	v_lshlrev_b32_e32 v68, 3, v2
	s_mov_b32 s32, 1
	s_branch .Lmy_p0_init
